# MLA: row-max partial chains moved into the QK MFMA shadows (recomputed after masking on diagonal tiles)
# baseline (speedup 1.0000x reference)
.LBB0_241:
	v_readlane_b32 s2, v253, 7
	s_add_i32 s58, s81, -2
	v_readlane_b32 s3, v253, 8
	s_mov_b32 s49, s3
	s_min_i32 s48, s58, s78
	s_lshl_b64 s[2:3], s[48:49], 17
	v_lshl_add_u64 v[2:3], v[200:201], 0, s[2:3]
	s_mov_b32 s2, 0x10000
	v_add_co_u32_e32 v4, vcc, s2, v2
	s_lshl_b64 s[2:3], s[48:49], 13
	s_nop 0
	v_addc_co_u32_e32 v5, vcc, 0, v3, vcc
	global_load_dwordx4 v[176:179], v[2:3], off
	global_load_dwordx4 v[180:183], v[4:5], off
	v_lshl_add_u64 v[2:3], v[202:203], 0, s[2:3]
	s_mov_b32 s3, s49
	v_writelane_b32 v253, s2, 7
	global_load_dwordx4 v[184:187], v[2:3], off
	s_add_i32 s62, s81, -5
	v_writelane_b32 v253, s3, 8
	s_lshl_b64 s[2:3], s[48:49], 8
	v_lshl_add_u64 v[2:3], v[204:205], 0, s[2:3]
	v_add_co_u32_e32 v4, vcc, 0x82000, v2
	s_xor_b64 s[64:65], s[8:9], -1
	s_nop 0
	v_addc_co_u32_e32 v5, vcc, 0, v3, vcc
	global_load_dwordx4 v[192:195], v[2:3], off
	global_load_dwordx4 v[188:191], v[4:5], off
	v_cmp_le_i32_e32 vcc, s62, v199
	v_add_u32_e32 v233, s81, v231
	s_and_b32 s59, s62, 1
	s_and_b64 s[2:3], s[64:65], vcc
	s_and_saveexec_b64 s[66:67], s[2:3]
	s_cbranch_execz .LBB0_259
	s_mul_i32 s2, s59, 0xac00
	v_or_b32_e32 v234, s2, v196
	v_add_u32_e32 v235, v234, v229
	ds_read_b128 v[2:5], v235
	ds_read_b128 v[6:9], v235 offset:32
	v_cmp_ge_i32_e32 vcc, s62, v199
	s_waitcnt lgkmcnt(1)
	v_mfma_f32_32x32x16_bf16 v[80:95], v[2:5], v[112:115], 0
	v_cndmask_b32_e32 v1, 3, v228, vcc
	s_waitcnt lgkmcnt(0)
	v_mfma_f32_32x32x16_bf16 v[80:95], v[6:9], v[116:119], v[80:95]
	ds_read_b128 v[2:5], v235 offset:64
	ds_read_b128 v[6:9], v235 offset:96
	s_waitcnt lgkmcnt(1)
	v_mfma_f32_32x32x16_bf16 v[80:95], v[2:5], v[120:123], v[80:95]
	ds_read_b128 v[2:5], v235 offset:128
	v_cmp_ne_u32_e64 s[52:53], 0, v1
	s_waitcnt lgkmcnt(1)
	v_mfma_f32_32x32x16_bf16 v[80:95], v[6:9], v[124:127], v[80:95]
	ds_read_b128 v[6:9], v235 offset:160
	s_waitcnt lgkmcnt(1)
	v_mfma_f32_32x32x16_bf16 v[80:95], v[2:5], v[128:131], v[80:95]
	s_waitcnt lgkmcnt(0)
	v_mfma_f32_32x32x16_bf16 v[80:95], v[6:9], v[132:135], v[80:95]
	s_and_saveexec_b64 s[48:49], s[52:53]
	s_cbranch_execz .Lmla_init_0
	ds_read_b128 v[2:5], v235 offset:6656
	ds_read_b128 v[212:215], v235 offset:6688
	ds_read_b128 v[216:219], v235 offset:6720
	ds_read_b128 v[220:223], v235 offset:6752
	s_waitcnt lgkmcnt(3)
	v_mfma_f32_32x32x16_bf16 v[96:111], v[2:5], v[112:115], 0
	ds_read_b128 v[2:5], v235 offset:6784
	s_waitcnt lgkmcnt(3)
	v_mfma_f32_32x32x16_bf16 v[96:111], v[212:215], v[116:119], v[96:111]
	ds_read_b128 v[212:215], v235 offset:6816
	s_waitcnt lgkmcnt(3)
	v_mfma_f32_32x32x16_bf16 v[96:111], v[216:219], v[120:123], v[96:111]
	v_max3_f32 v241, v80, v81, v82
	v_max3_f32 v241, v241, v83, v84
	s_waitcnt lgkmcnt(2)
	v_mfma_f32_32x32x16_bf16 v[96:111], v[220:223], v[124:127], v[96:111]
	v_max3_f32 v241, v241, v85, v86
	v_max3_f32 v241, v241, v87, v88
	s_waitcnt lgkmcnt(1)
	v_mfma_f32_32x32x16_bf16 v[96:111], v[2:5], v[128:131], v[96:111]
	v_max3_f32 v241, v241, v89, v90
	v_max3_f32 v241, v241, v91, v92
	s_waitcnt lgkmcnt(0)
	v_mfma_f32_32x32x16_bf16 v[96:111], v[212:215], v[132:135], v[96:111]
	v_max3_f32 v241, v241, v93, v94
	v_max_f32_e32 v241, v241, v95
.LBB0_244:
	s_or_b64 exec, exec, s[48:49]
	v_cmp_lt_u32_e64 s[50:51], 1, v1
	s_and_saveexec_b64 s[48:49], s[50:51]
	s_cbranch_execz .Lmla_init_1
	ds_read_b128 v[2:5], v235 offset:13312
	ds_read_b128 v[212:215], v235 offset:13344
	ds_read_b128 v[216:219], v235 offset:13376
	ds_read_b128 v[220:223], v235 offset:13408
	s_waitcnt lgkmcnt(3)
	v_mfma_f32_32x32x16_bf16 v[48:63], v[2:5], v[112:115], 0
	ds_read_b128 v[2:5], v235 offset:13440
	s_waitcnt lgkmcnt(3)
	v_mfma_f32_32x32x16_bf16 v[48:63], v[212:215], v[116:119], v[48:63]
	ds_read_b128 v[212:215], v235 offset:13472
	s_waitcnt lgkmcnt(3)
	v_mfma_f32_32x32x16_bf16 v[48:63], v[216:219], v[120:123], v[48:63]
	v_max3_f32 v242, v96, v97, v98
	v_max3_f32 v242, v242, v99, v100
	s_waitcnt lgkmcnt(2)
	v_mfma_f32_32x32x16_bf16 v[48:63], v[220:223], v[124:127], v[48:63]
	v_max3_f32 v242, v242, v101, v102
	v_max3_f32 v242, v242, v103, v104
	s_waitcnt lgkmcnt(1)
	v_mfma_f32_32x32x16_bf16 v[48:63], v[2:5], v[128:131], v[48:63]
	v_max3_f32 v242, v242, v105, v106
	v_max3_f32 v242, v242, v107, v108
	s_waitcnt lgkmcnt(0)
	v_mfma_f32_32x32x16_bf16 v[48:63], v[212:215], v[132:135], v[48:63]
	v_max3_f32 v242, v242, v109, v110
	v_max_f32_e32 v242, v242, v111
.LBB0_246:
	s_or_b64 exec, exec, s[48:49]
	v_cmp_eq_u32_e64 s[48:49], 3, v1
	s_and_saveexec_b64 s[56:57], s[48:49]
	s_cbranch_execz .Lmla_init_2
	ds_read_b128 v[2:5], v235 offset:19968
	ds_read_b128 v[212:215], v235 offset:20000
	ds_read_b128 v[216:219], v235 offset:20032
	ds_read_b128 v[220:223], v235 offset:20064
	s_waitcnt lgkmcnt(3)
	v_mfma_f32_32x32x16_bf16 v[64:79], v[2:5], v[112:115], 0
	ds_read_b128 v[2:5], v235 offset:20096
	s_waitcnt lgkmcnt(3)
	v_mfma_f32_32x32x16_bf16 v[64:79], v[212:215], v[116:119], v[64:79]
	ds_read_b128 v[212:215], v235 offset:20128
	s_waitcnt lgkmcnt(3)
	v_mfma_f32_32x32x16_bf16 v[64:79], v[216:219], v[120:123], v[64:79]
	v_max3_f32 v243, v48, v49, v50
	v_max3_f32 v243, v243, v51, v52
	s_waitcnt lgkmcnt(2)
	v_mfma_f32_32x32x16_bf16 v[64:79], v[220:223], v[124:127], v[64:79]
	v_max3_f32 v243, v243, v53, v54
	v_max3_f32 v243, v243, v55, v56
	s_waitcnt lgkmcnt(1)
	v_mfma_f32_32x32x16_bf16 v[64:79], v[2:5], v[128:131], v[64:79]
	v_max3_f32 v243, v243, v57, v58
	v_max3_f32 v243, v243, v59, v60
	s_waitcnt lgkmcnt(0)
	v_mfma_f32_32x32x16_bf16 v[64:79], v[212:215], v[132:135], v[64:79]
	v_max3_f32 v243, v243, v61, v62
	v_max_f32_e32 v243, v243, v63
.LBB0_248:
	s_or_b64 exec, exec, s[56:57]
	s_cmp_eq_u32 s79, 0
	s_movk_i32 s56, 0x45
	s_cselect_b64 s[2:3], -1, 0
	v_cmp_eq_u32_e32 vcc, s56, v233
	s_or_b64 s[2:3], s[2:3], vcc
	s_and_saveexec_b64 s[70:71], s[2:3]
	s_cbranch_execz .LBB0_250
	v_add_u32_e32 v1, s79, v207
	s_cmp_lg_u32 s79, 0
	v_cmp_le_i32_e32 vcc, v1, v198
	s_cselect_b64 s[2:3], -1, 0
	s_and_b64 vcc, s[2:3], vcc
	v_cndmask_b32_e32 v80, v0, v80, vcc
	v_cmp_lt_i32_e32 vcc, v1, v198
	s_and_b64 vcc, s[2:3], vcc
	v_add_u32_e32 v2, 2, v1
	v_cndmask_b32_e32 v81, v0, v81, vcc
	v_cmp_le_i32_e32 vcc, v2, v198
	s_and_b64 vcc, s[2:3], vcc
	v_add_u32_e32 v2, 3, v1
	v_cndmask_b32_e32 v82, v0, v82, vcc
	v_cmp_le_i32_e32 vcc, v2, v198
	s_and_b64 vcc, s[2:3], vcc
	v_add_u32_e32 v2, 8, v1
	v_cndmask_b32_e32 v83, v0, v83, vcc
	v_cmp_le_i32_e32 vcc, v2, v198
	s_and_b64 vcc, s[2:3], vcc
	v_add_u32_e32 v2, 9, v1
	v_cndmask_b32_e32 v84, v0, v84, vcc
	v_cmp_le_i32_e32 vcc, v2, v198
	s_and_b64 vcc, s[2:3], vcc
	v_add_u32_e32 v2, 10, v1
	v_cndmask_b32_e32 v85, v0, v85, vcc
	v_cmp_le_i32_e32 vcc, v2, v198
	s_and_b64 vcc, s[2:3], vcc
	v_add_u32_e32 v2, 11, v1
	v_cndmask_b32_e32 v86, v0, v86, vcc
	v_cmp_le_i32_e32 vcc, v2, v198
	s_and_b64 vcc, s[2:3], vcc
	v_add_u32_e32 v2, 16, v1
	s_movk_i32 s2, 0x6f
	v_cndmask_b32_e32 v87, v0, v87, vcc
	v_cmp_le_i32_e64 s[56:57], v2, v198
	v_cmp_lt_u32_e32 vcc, s2, v2
	s_and_b64 vcc, s[56:57], vcc
	v_add_u32_e32 v2, 17, v1
	v_cndmask_b32_e32 v88, v0, v88, vcc
	v_cmp_le_i32_e32 vcc, v2, v198
	v_cmp_lt_u32_e64 s[56:57], s2, v2
	s_and_b64 vcc, vcc, s[56:57]
	v_add_u32_e32 v2, 18, v1
	v_cndmask_b32_e32 v89, v0, v89, vcc
	v_cmp_le_i32_e32 vcc, v2, v198
	v_cmp_lt_u32_e64 s[56:57], s2, v2
	s_and_b64 vcc, vcc, s[56:57]
	v_add_u32_e32 v2, 19, v1
	v_cndmask_b32_e32 v90, v0, v90, vcc
	v_cmp_le_i32_e32 vcc, v2, v198
	v_cmp_lt_u32_e64 s[56:57], s2, v2
	s_and_b64 vcc, vcc, s[56:57]
	v_add_u32_e32 v2, 24, v1
	v_cndmask_b32_e32 v91, v0, v91, vcc
	v_cmp_le_i32_e32 vcc, v2, v198
	v_cmp_lt_u32_e64 s[56:57], s2, v2
	s_and_b64 vcc, vcc, s[56:57]
	v_add_u32_e32 v2, 25, v1
	v_cndmask_b32_e32 v92, v0, v92, vcc
	v_cmp_le_i32_e32 vcc, v2, v198
	v_cmp_lt_u32_e64 s[56:57], s2, v2
	s_and_b64 vcc, vcc, s[56:57]
	v_add_u32_e32 v2, 26, v1
	v_cndmask_b32_e32 v93, v0, v93, vcc
	v_cmp_le_i32_e32 vcc, v2, v198
	v_cmp_lt_u32_e64 s[56:57], s2, v2
	s_and_b64 vcc, vcc, s[56:57]
	v_add_u32_e32 v2, 27, v1
	v_cndmask_b32_e32 v94, v0, v94, vcc
	v_cmp_le_i32_e32 vcc, v2, v198
	v_cmp_lt_u32_e64 s[56:57], s2, v2
	s_and_b64 vcc, vcc, s[56:57]
	v_add_u32_e32 v2, 32, v1
	v_cndmask_b32_e32 v95, v0, v95, vcc
	v_cmp_le_i32_e32 vcc, v2, v198
	v_cmp_lt_u32_e64 s[56:57], s2, v2
	s_and_b64 vcc, vcc, s[56:57]
	v_add_u32_e32 v2, 33, v1
	v_cndmask_b32_e32 v96, v0, v96, vcc
	v_cmp_le_i32_e32 vcc, v2, v198
	v_cmp_lt_u32_e64 s[56:57], s2, v2
	s_and_b64 vcc, vcc, s[56:57]
	v_add_u32_e32 v2, 34, v1
	v_cndmask_b32_e32 v97, v0, v97, vcc
	v_cmp_le_i32_e32 vcc, v2, v198
	v_cmp_lt_u32_e64 s[56:57], s2, v2
	s_and_b64 vcc, vcc, s[56:57]
	v_add_u32_e32 v2, 35, v1
	v_cndmask_b32_e32 v98, v0, v98, vcc
	v_cmp_le_i32_e32 vcc, v2, v198
	v_cmp_lt_u32_e64 s[56:57], s2, v2
	s_and_b64 vcc, vcc, s[56:57]
	v_add_u32_e32 v2, 40, v1
	v_cndmask_b32_e32 v99, v0, v99, vcc
	v_cmp_le_i32_e32 vcc, v2, v198
	v_cmp_lt_u32_e64 s[56:57], s2, v2
	s_and_b64 vcc, vcc, s[56:57]
	v_add_u32_e32 v2, 41, v1
	v_cndmask_b32_e32 v100, v0, v100, vcc
	v_cmp_le_i32_e32 vcc, v2, v198
	v_cmp_lt_u32_e64 s[56:57], s2, v2
	s_and_b64 vcc, vcc, s[56:57]
	v_add_u32_e32 v2, 42, v1
	v_cndmask_b32_e32 v101, v0, v101, vcc
	v_cmp_le_i32_e32 vcc, v2, v198
	v_cmp_lt_u32_e64 s[56:57], s2, v2
	s_and_b64 vcc, vcc, s[56:57]
	v_add_u32_e32 v2, 43, v1
	v_cndmask_b32_e32 v102, v0, v102, vcc
	v_cmp_le_i32_e32 vcc, v2, v198
	v_cmp_lt_u32_e64 s[56:57], s2, v2
	s_and_b64 vcc, vcc, s[56:57]
	v_add_u32_e32 v2, 48, v1
	v_cndmask_b32_e32 v103, v0, v103, vcc
	v_cmp_le_i32_e32 vcc, v2, v198
	v_cmp_lt_u32_e64 s[56:57], s2, v2
	s_and_b64 vcc, vcc, s[56:57]
	v_add_u32_e32 v2, 49, v1
	v_cndmask_b32_e32 v104, v0, v104, vcc
	v_cmp_le_i32_e32 vcc, v2, v198
	v_cmp_lt_u32_e64 s[56:57], s2, v2
	s_and_b64 vcc, vcc, s[56:57]
	v_add_u32_e32 v2, 50, v1
	v_cndmask_b32_e32 v105, v0, v105, vcc
	v_cmp_le_i32_e32 vcc, v2, v198
	v_cmp_lt_u32_e64 s[56:57], s2, v2
	s_and_b64 vcc, vcc, s[56:57]
	v_add_u32_e32 v2, 51, v1
	v_cndmask_b32_e32 v106, v0, v106, vcc
	v_cmp_le_i32_e32 vcc, v2, v198
	v_cmp_lt_u32_e64 s[56:57], s2, v2
	s_and_b64 vcc, vcc, s[56:57]
	v_add_u32_e32 v2, 56, v1
	v_cndmask_b32_e32 v107, v0, v107, vcc
	v_cmp_le_i32_e32 vcc, v2, v198
	v_cmp_lt_u32_e64 s[56:57], s2, v2
	s_and_b64 vcc, vcc, s[56:57]
	v_add_u32_e32 v2, 57, v1
	v_cndmask_b32_e32 v108, v0, v108, vcc
	v_cmp_le_i32_e32 vcc, v2, v198
	v_cmp_lt_u32_e64 s[56:57], s2, v2
	s_and_b64 vcc, vcc, s[56:57]
	v_add_u32_e32 v2, 58, v1
	v_cndmask_b32_e32 v109, v0, v109, vcc
	v_cmp_le_i32_e32 vcc, v2, v198
	v_cmp_lt_u32_e64 s[56:57], s2, v2
	s_and_b64 vcc, vcc, s[56:57]
	v_add_u32_e32 v2, 59, v1
	v_cndmask_b32_e32 v110, v0, v110, vcc
	v_cmp_le_i32_e32 vcc, v2, v198
	v_cmp_lt_u32_e64 s[56:57], s2, v2
	s_and_b64 vcc, vcc, s[56:57]
	v_add_u32_e32 v2, 64, v1
	v_cndmask_b32_e32 v111, v0, v111, vcc
	v_cmp_le_i32_e32 vcc, v2, v198
	v_cmp_lt_u32_e64 s[56:57], s2, v2
	s_and_b64 vcc, vcc, s[56:57]
	v_add_u32_e32 v2, 0x41, v1
	v_cndmask_b32_e32 v48, v0, v48, vcc
	v_cmp_le_i32_e32 vcc, v2, v198
	v_cmp_lt_u32_e64 s[56:57], s2, v2
	s_and_b64 vcc, vcc, s[56:57]
	v_add_u32_e32 v2, 0x42, v1
	v_cndmask_b32_e32 v49, v0, v49, vcc
	v_cmp_le_i32_e32 vcc, v2, v198
	v_cmp_lt_u32_e64 s[56:57], s2, v2
	s_and_b64 vcc, vcc, s[56:57]
	v_add_u32_e32 v2, 0x43, v1
	v_cndmask_b32_e32 v50, v0, v50, vcc
	v_cmp_le_i32_e32 vcc, v2, v198
	v_cmp_lt_u32_e64 s[56:57], s2, v2
	s_and_b64 vcc, vcc, s[56:57]
	v_add_u32_e32 v2, 0x48, v1
	v_cndmask_b32_e32 v51, v0, v51, vcc
	v_cmp_le_i32_e32 vcc, v2, v198
	v_cmp_lt_u32_e64 s[56:57], s2, v2
	s_and_b64 vcc, vcc, s[56:57]
	v_add_u32_e32 v2, 0x49, v1
	v_cndmask_b32_e32 v52, v0, v52, vcc
	v_cmp_le_i32_e32 vcc, v2, v198
	v_cmp_lt_u32_e64 s[56:57], s2, v2
	s_and_b64 vcc, vcc, s[56:57]
	v_add_u32_e32 v2, 0x4a, v1
	v_cndmask_b32_e32 v53, v0, v53, vcc
	v_cmp_le_i32_e32 vcc, v2, v198
	v_cmp_lt_u32_e64 s[56:57], s2, v2
	s_and_b64 vcc, vcc, s[56:57]
	v_add_u32_e32 v2, 0x4b, v1
	v_cndmask_b32_e32 v54, v0, v54, vcc
	v_cmp_le_i32_e32 vcc, v2, v198
	v_cmp_lt_u32_e64 s[56:57], s2, v2
	s_and_b64 vcc, vcc, s[56:57]
	v_add_u32_e32 v2, 0x50, v1
	v_cndmask_b32_e32 v55, v0, v55, vcc
	v_cmp_le_i32_e32 vcc, v2, v198
	v_cmp_lt_u32_e64 s[56:57], s2, v2
	s_and_b64 vcc, vcc, s[56:57]
	v_add_u32_e32 v2, 0x51, v1
	v_cndmask_b32_e32 v56, v0, v56, vcc
	v_cmp_le_i32_e32 vcc, v2, v198
	v_cmp_lt_u32_e64 s[56:57], s2, v2
	s_and_b64 vcc, vcc, s[56:57]
	v_add_u32_e32 v2, 0x52, v1
	v_cndmask_b32_e32 v57, v0, v57, vcc
	v_cmp_le_i32_e32 vcc, v2, v198
	v_cmp_lt_u32_e64 s[56:57], s2, v2
	s_and_b64 vcc, vcc, s[56:57]
	v_add_u32_e32 v2, 0x53, v1
	v_cndmask_b32_e32 v58, v0, v58, vcc
	v_cmp_le_i32_e32 vcc, v2, v198
	v_cmp_lt_u32_e64 s[56:57], s2, v2
	s_and_b64 vcc, vcc, s[56:57]
	v_add_u32_e32 v2, 0x58, v1
	v_cndmask_b32_e32 v59, v0, v59, vcc
	v_cmp_le_i32_e32 vcc, v2, v198
	v_cmp_lt_u32_e64 s[56:57], s2, v2
	s_and_b64 vcc, vcc, s[56:57]
	v_add_u32_e32 v2, 0x59, v1
	v_cndmask_b32_e32 v60, v0, v60, vcc
	v_cmp_le_i32_e32 vcc, v2, v198
	v_cmp_lt_u32_e64 s[56:57], s2, v2
	s_and_b64 vcc, vcc, s[56:57]
	v_add_u32_e32 v2, 0x5a, v1
	v_cndmask_b32_e32 v61, v0, v61, vcc
	v_cmp_le_i32_e32 vcc, v2, v198
	v_cmp_lt_u32_e64 s[56:57], s2, v2
	s_and_b64 vcc, vcc, s[56:57]
	v_add_u32_e32 v2, 0x5b, v1
	v_cndmask_b32_e32 v62, v0, v62, vcc
	v_cmp_le_i32_e32 vcc, v2, v198
	v_cmp_lt_u32_e64 s[56:57], s2, v2
	s_and_b64 vcc, vcc, s[56:57]
	v_add_u32_e32 v2, 0x60, v1
	v_cndmask_b32_e32 v63, v0, v63, vcc
	v_cmp_le_i32_e32 vcc, v2, v198
	v_cmp_lt_u32_e64 s[56:57], s2, v2
	s_and_b64 vcc, vcc, s[56:57]
	v_add_u32_e32 v2, 0x61, v1
	v_cndmask_b32_e32 v64, v0, v64, vcc
	v_cmp_le_i32_e32 vcc, v2, v198
	v_cmp_lt_u32_e64 s[56:57], s2, v2
	s_and_b64 vcc, vcc, s[56:57]
	v_add_u32_e32 v2, 0x62, v1
	v_cndmask_b32_e32 v65, v0, v65, vcc
	v_cmp_le_i32_e32 vcc, v2, v198
	v_cmp_lt_u32_e64 s[56:57], s2, v2
	s_and_b64 vcc, vcc, s[56:57]
	v_add_u32_e32 v2, 0x63, v1
	v_cndmask_b32_e32 v66, v0, v66, vcc
	v_cmp_le_i32_e32 vcc, v2, v198
	v_cmp_lt_u32_e64 s[56:57], s2, v2
	s_and_b64 vcc, vcc, s[56:57]
	v_add_u32_e32 v2, 0x68, v1
	v_cndmask_b32_e32 v67, v0, v67, vcc
	v_cmp_le_i32_e32 vcc, v2, v198
	v_cmp_lt_u32_e64 s[56:57], s2, v2
	s_and_b64 vcc, vcc, s[56:57]
	v_add_u32_e32 v2, 0x69, v1
	v_cndmask_b32_e32 v68, v0, v68, vcc
	v_cmp_le_i32_e32 vcc, v2, v198
	v_cmp_lt_u32_e64 s[56:57], s2, v2
	s_and_b64 vcc, vcc, s[56:57]
	v_add_u32_e32 v2, 0x6a, v1
	v_cndmask_b32_e32 v69, v0, v69, vcc
	v_cmp_le_i32_e32 vcc, v2, v198
	v_cmp_lt_u32_e64 s[56:57], s2, v2
	s_and_b64 vcc, vcc, s[56:57]
	v_add_u32_e32 v2, 0x6b, v1
	v_cndmask_b32_e32 v70, v0, v70, vcc
	v_cmp_le_i32_e32 vcc, v2, v198
	v_cmp_lt_u32_e64 s[56:57], s2, v2
	s_and_b64 vcc, vcc, s[56:57]
	v_add_u32_e32 v2, 0x70, v1
	v_cndmask_b32_e32 v71, v0, v71, vcc
	v_cmp_le_i32_e32 vcc, v2, v198
	v_add_u32_e32 v2, 0x71, v1
	s_nop 0
	v_cndmask_b32_e32 v72, v0, v72, vcc
	v_cmp_le_i32_e32 vcc, v2, v198
	v_add_u32_e32 v2, 0x72, v1
	s_nop 0
	v_cndmask_b32_e32 v73, v0, v73, vcc
	v_cmp_le_i32_e32 vcc, v2, v198
	v_add_u32_e32 v2, 0x73, v1
	s_nop 0
	v_cndmask_b32_e32 v74, v0, v74, vcc
	v_cmp_le_i32_e32 vcc, v2, v198
	v_add_u32_e32 v2, 0x78, v1
	s_nop 0
	v_cndmask_b32_e32 v75, v0, v75, vcc
	v_cmp_le_i32_e32 vcc, v2, v198
	v_add_u32_e32 v2, 0x79, v1
	s_nop 0
	v_cndmask_b32_e32 v76, v0, v76, vcc
	v_cmp_le_i32_e32 vcc, v2, v198
	v_add_u32_e32 v2, 0x7a, v1
	v_add_u32_e32 v1, 0x7b, v1
	v_cndmask_b32_e32 v77, v0, v77, vcc
	v_cmp_le_i32_e32 vcc, v2, v198
	s_nop 1
	v_cndmask_b32_e32 v78, v0, v78, vcc
	v_cmp_le_i32_e32 vcc, v1, v198
	s_nop 1
	v_cndmask_b32_e32 v79, v0, v79, vcc
	v_max3_f32 v241, v80, v81, v82
	v_max3_f32 v241, v241, v83, v84
	v_max3_f32 v241, v241, v85, v86
	v_max3_f32 v241, v241, v87, v88
	v_max3_f32 v241, v241, v89, v90
	v_max3_f32 v241, v241, v91, v92
	v_max3_f32 v241, v241, v93, v94
	v_max_f32_e32 v241, v241, v95
	v_max3_f32 v242, v96, v97, v98
	v_max3_f32 v242, v242, v99, v100
	v_max3_f32 v242, v242, v101, v102
	v_max3_f32 v242, v242, v103, v104
	v_max3_f32 v242, v242, v105, v106
	v_max3_f32 v242, v242, v107, v108
	v_max3_f32 v242, v242, v109, v110
	v_max_f32_e32 v242, v242, v111
	v_max3_f32 v243, v48, v49, v50
	v_max3_f32 v243, v243, v51, v52
	v_max3_f32 v243, v243, v53, v54
	v_max3_f32 v243, v243, v55, v56
	v_max3_f32 v243, v243, v57, v58
	v_max3_f32 v243, v243, v59, v60
	v_max3_f32 v243, v243, v61, v62
	v_max_f32_e32 v243, v243, v63
.LBB0_250:
	s_or_b64 exec, exec, s[70:71]
	s_nop 3
	v_max3_f32 v4, v64, v65, v66
	v_max3_f32 v4, v4, v67, v68
	v_max3_f32 v4, v4, v69, v70
	v_max3_f32 v4, v4, v71, v72
	v_max3_f32 v4, v4, v73, v74
	v_max3_f32 v4, v4, v75, v76
	v_max3_f32 v4, v4, v77, v78
	v_max_f32_e32 v4, v4, v79
	v_max3_f32 v1, v241, v242, v243
	v_max_f32_e32 v1, v1, v4
	v_mov_b32_e32 v2, v1
	s_nop 1
	v_permlane32_swap_b32_e32 v2, v1
	s_nop 0
	v_max3_f32 v1, v238, v1, v2
	v_sub_f32_e32 v2, v238, v1
	v_exp_f32_e32 v2, v2
	v_cmp_gt_f32_e32 vcc, v1, v238
	s_cbranch_vccz .LBB0_252
	v_pk_mul_f32 v[46:47], v[46:47], v[2:3] op_sel_hi:[1,0]
	v_pk_mul_f32 v[44:45], v[44:45], v[2:3] op_sel_hi:[1,0]
	v_pk_mul_f32 v[42:43], v[42:43], v[2:3] op_sel_hi:[1,0]
	v_pk_mul_f32 v[40:41], v[40:41], v[2:3] op_sel_hi:[1,0]
	v_pk_mul_f32 v[38:39], v[38:39], v[2:3] op_sel_hi:[1,0]
	v_pk_mul_f32 v[36:37], v[36:37], v[2:3] op_sel_hi:[1,0]
	v_pk_mul_f32 v[34:35], v[34:35], v[2:3] op_sel_hi:[1,0]
	v_pk_mul_f32 v[32:33], v[32:33], v[2:3] op_sel_hi:[1,0]
	v_pk_mul_f32 v[30:31], v[30:31], v[2:3] op_sel_hi:[1,0]
	v_pk_mul_f32 v[28:29], v[28:29], v[2:3] op_sel_hi:[1,0]
	v_pk_mul_f32 v[26:27], v[26:27], v[2:3] op_sel_hi:[1,0]
	v_pk_mul_f32 v[24:25], v[24:25], v[2:3] op_sel_hi:[1,0]
	v_pk_mul_f32 v[22:23], v[22:23], v[2:3] op_sel_hi:[1,0]
	v_pk_mul_f32 v[20:21], v[20:21], v[2:3] op_sel_hi:[1,0]
	v_pk_mul_f32 v[18:19], v[18:19], v[2:3] op_sel_hi:[1,0]
	v_pk_mul_f32 v[16:17], v[16:17], v[2:3] op_sel_hi:[1,0]

.LBB0_259:
	s_or_b64 exec, exec, s[66:67]
	s_xor_b32 s2, s59, 1
	s_mul_i32 s2, s2, 0xac00
	v_lshl_add_u32 v1, v209, 1, s2
	s_cmp_lt_u32 s62, s78
	v_lshl_add_u32 v234, v206, 1, s2
	v_lshl_add_u32 v235, v208, 1, s2
	v_add_u32_e32 v236, 0x6800, v1
	v_add_u32_e32 v237, 0x8800, v1
	s_cselect_b64 s[56:57], -1, 0
	s_cmp_ge_u32 s62, s78
	s_waitcnt vmcnt(9)
	ds_write_b128 v234, v[136:139]
	s_waitcnt vmcnt(8)
	ds_write_b128 v234, v[140:143] offset:13312
	s_waitcnt vmcnt(7)
	ds_write_b128 v235, v[148:151] offset:128
	s_waitcnt vmcnt(6)
	ds_write2_b64 v236, v[152:153], v[154:155] offset1:2
	s_waitcnt vmcnt(5)
	ds_write2_b64 v237, v[160:161], v[162:163] offset0:64 offset1:66
	s_waitcnt lgkmcnt(0)
	s_barrier
	s_cbranch_scc1 .LBB0_279
	s_add_i32 s2, s81, -1
	v_readlane_b32 s48, v253, 7
	v_readlane_b32 s49, v253, 8
	s_min_i32 s48, s2, s78
	s_lshl_b64 s[2:3], s[48:49], 17
	v_lshl_add_u64 v[2:3], v[200:201], 0, s[2:3]
	v_add_co_u32_e32 v4, vcc, 0x10000, v2
	s_lshl_b64 s[2:3], s[48:49], 13
	s_nop 0
	v_addc_co_u32_e32 v5, vcc, 0, v3, vcc
	global_load_dwordx4 v[136:139], v[2:3], off
	global_load_dwordx4 v[140:143], v[4:5], off
	v_lshl_add_u64 v[2:3], v[202:203], 0, s[2:3]
	s_mov_b32 s3, s49
	v_writelane_b32 v253, s2, 7
	global_load_dwordx4 v[148:151], v[2:3], off
	s_nop 0
	v_writelane_b32 v253, s3, 8
	s_lshl_b64 s[2:3], s[48:49], 8
	v_lshl_add_u64 v[2:3], v[204:205], 0, s[2:3]
	v_add_co_u32_e32 v4, vcc, 0x82000, v2
	s_add_i32 s3, s81, -4
	s_nop 0
	v_addc_co_u32_e32 v5, vcc, 0, v3, vcc
	global_load_dwordx4 v[152:155], v[2:3], off
	global_load_dwordx4 v[160:163], v[4:5], off
	v_cmp_lt_i32_e32 vcc, s62, v199
	s_and_b32 s2, s3, 1
	s_and_b64 s[48:49], s[64:65], vcc
	s_and_saveexec_b64 s[66:67], s[48:49]
	s_cbranch_execz .LBB0_278
	s_mul_i32 s48, s2, 0xac00
	v_or_b32_e32 v239, s48, v196
	v_add_u32_e32 v240, v239, v229
	ds_read_b128 v[2:5], v240
	ds_read_b128 v[6:9], v240 offset:32
	v_cmp_ge_i32_e32 vcc, s3, v199
	s_waitcnt lgkmcnt(1)
	v_mfma_f32_32x32x16_bf16 v[80:95], v[2:5], v[112:115], 0
	v_cndmask_b32_e32 v1, 3, v228, vcc
	s_waitcnt lgkmcnt(0)
	v_mfma_f32_32x32x16_bf16 v[80:95], v[6:9], v[116:119], v[80:95]
	ds_read_b128 v[2:5], v240 offset:64
	ds_read_b128 v[6:9], v240 offset:96
	s_waitcnt lgkmcnt(1)
	v_mfma_f32_32x32x16_bf16 v[80:95], v[2:5], v[120:123], v[80:95]
	ds_read_b128 v[2:5], v240 offset:128
	v_cmp_ne_u32_e64 s[52:53], 0, v1
	s_waitcnt lgkmcnt(1)
	v_mfma_f32_32x32x16_bf16 v[80:95], v[6:9], v[124:127], v[80:95]
	ds_read_b128 v[6:9], v240 offset:160
	s_waitcnt lgkmcnt(1)
	v_mfma_f32_32x32x16_bf16 v[80:95], v[2:5], v[128:131], v[80:95]
	s_waitcnt lgkmcnt(0)
	v_mfma_f32_32x32x16_bf16 v[80:95], v[6:9], v[132:135], v[80:95]
	s_and_saveexec_b64 s[48:49], s[52:53]
	s_cbranch_execz .Lmla_init_3
	ds_read_b128 v[2:5], v240 offset:6656
	ds_read_b128 v[212:215], v240 offset:6688
	ds_read_b128 v[216:219], v240 offset:6720
	ds_read_b128 v[220:223], v240 offset:6752
	s_waitcnt lgkmcnt(3)
	v_mfma_f32_32x32x16_bf16 v[96:111], v[2:5], v[112:115], 0
	ds_read_b128 v[2:5], v240 offset:6784
	s_waitcnt lgkmcnt(3)
	v_mfma_f32_32x32x16_bf16 v[96:111], v[212:215], v[116:119], v[96:111]
	ds_read_b128 v[212:215], v240 offset:6816
	s_waitcnt lgkmcnt(3)
	v_mfma_f32_32x32x16_bf16 v[96:111], v[216:219], v[120:123], v[96:111]
	v_max3_f32 v241, v80, v81, v82
	v_max3_f32 v241, v241, v83, v84
	s_waitcnt lgkmcnt(2)
	v_mfma_f32_32x32x16_bf16 v[96:111], v[220:223], v[124:127], v[96:111]
	v_max3_f32 v241, v241, v85, v86
	v_max3_f32 v241, v241, v87, v88
	s_waitcnt lgkmcnt(1)
	v_mfma_f32_32x32x16_bf16 v[96:111], v[2:5], v[128:131], v[96:111]
	v_max3_f32 v241, v241, v89, v90
	v_max3_f32 v241, v241, v91, v92
	s_waitcnt lgkmcnt(0)
	v_mfma_f32_32x32x16_bf16 v[96:111], v[212:215], v[132:135], v[96:111]
	v_max3_f32 v241, v241, v93, v94
	v_max_f32_e32 v241, v241, v95
.LBB0_263:
	s_or_b64 exec, exec, s[48:49]
	v_cmp_lt_u32_e64 s[50:51], 1, v1
	s_and_saveexec_b64 s[48:49], s[50:51]
	s_cbranch_execz .Lmla_init_4
	ds_read_b128 v[2:5], v240 offset:13312
	ds_read_b128 v[212:215], v240 offset:13344
	ds_read_b128 v[216:219], v240 offset:13376
	ds_read_b128 v[220:223], v240 offset:13408
	s_waitcnt lgkmcnt(3)
	v_mfma_f32_32x32x16_bf16 v[48:63], v[2:5], v[112:115], 0
	ds_read_b128 v[2:5], v240 offset:13440
	s_waitcnt lgkmcnt(3)
	v_mfma_f32_32x32x16_bf16 v[48:63], v[212:215], v[116:119], v[48:63]
	ds_read_b128 v[212:215], v240 offset:13472
	s_waitcnt lgkmcnt(3)
	v_mfma_f32_32x32x16_bf16 v[48:63], v[216:219], v[120:123], v[48:63]
	v_max3_f32 v242, v96, v97, v98
	v_max3_f32 v242, v242, v99, v100
	s_waitcnt lgkmcnt(2)
	v_mfma_f32_32x32x16_bf16 v[48:63], v[220:223], v[124:127], v[48:63]
	v_max3_f32 v242, v242, v101, v102
	v_max3_f32 v242, v242, v103, v104
	s_waitcnt lgkmcnt(1)
	v_mfma_f32_32x32x16_bf16 v[48:63], v[2:5], v[128:131], v[48:63]
	v_max3_f32 v242, v242, v105, v106
	v_max3_f32 v242, v242, v107, v108
	s_waitcnt lgkmcnt(0)
	v_mfma_f32_32x32x16_bf16 v[48:63], v[212:215], v[132:135], v[48:63]
	v_max3_f32 v242, v242, v109, v110
	v_max_f32_e32 v242, v242, v111
.LBB0_265:
	s_or_b64 exec, exec, s[48:49]
	v_cmp_eq_u32_e64 s[48:49], 3, v1
	s_and_saveexec_b64 s[62:63], s[48:49]
	s_cbranch_execz .Lmla_init_5
	ds_read_b128 v[2:5], v240 offset:19968
	ds_read_b128 v[212:215], v240 offset:20000
	ds_read_b128 v[216:219], v240 offset:20032
	ds_read_b128 v[220:223], v240 offset:20064
	s_waitcnt lgkmcnt(3)
	v_mfma_f32_32x32x16_bf16 v[64:79], v[2:5], v[112:115], 0
	ds_read_b128 v[2:5], v240 offset:20096
	s_waitcnt lgkmcnt(3)
	v_mfma_f32_32x32x16_bf16 v[64:79], v[212:215], v[116:119], v[64:79]
	ds_read_b128 v[212:215], v240 offset:20128
	s_waitcnt lgkmcnt(3)
	v_mfma_f32_32x32x16_bf16 v[64:79], v[216:219], v[120:123], v[64:79]
	v_max3_f32 v243, v48, v49, v50
	v_max3_f32 v243, v243, v51, v52
	s_waitcnt lgkmcnt(2)
	v_mfma_f32_32x32x16_bf16 v[64:79], v[220:223], v[124:127], v[64:79]
	v_max3_f32 v243, v243, v53, v54
	v_max3_f32 v243, v243, v55, v56
	s_waitcnt lgkmcnt(1)
	v_mfma_f32_32x32x16_bf16 v[64:79], v[2:5], v[128:131], v[64:79]
	v_max3_f32 v243, v243, v57, v58
	v_max3_f32 v243, v243, v59, v60
	s_waitcnt lgkmcnt(0)
	v_mfma_f32_32x32x16_bf16 v[64:79], v[212:215], v[132:135], v[64:79]
	v_max3_f32 v243, v243, v61, v62
	v_max_f32_e32 v243, v243, v63
.LBB0_267:
	s_or_b64 exec, exec, s[62:63]
	s_movk_i32 s3, 0x44
	v_cmp_eq_u32_e32 vcc, s3, v233
	s_and_saveexec_b64 s[70:71], vcc
	s_cbranch_execz .LBB0_269
	v_readlane_b32 s62, v253, 53
	v_readlane_b32 s63, v253, 54
	v_cndmask_b32_e64 v81, v0, v81, s[12:13]
	v_cndmask_b32_e64 v52, v52, v0, s[84:85]
	v_cndmask_b32_e64 v1, v80, v0, s[62:63]
	v_readlane_b32 s62, v253, 55
	v_readlane_b32 s63, v253, 56
	v_cndmask_b32_e64 v80, v1, v80, s[12:13]
	v_cndmask_b32_e64 v53, v53, v0, s[86:87]
	v_cndmask_b32_e64 v82, v82, v0, s[62:63]
	v_readlane_b32 s62, v253, 57
	v_readlane_b32 s63, v253, 58
	v_cndmask_b32_e64 v54, v54, v0, s[88:89]
	v_cndmask_b32_e64 v55, v55, v0, s[90:91]
	v_cndmask_b32_e64 v83, v83, v0, s[62:63]
	v_readlane_b32 s62, v253, 61
	v_readlane_b32 s63, v253, 62
	v_cndmask_b32_e64 v56, v56, v0, s[92:93]
	v_cndmask_b32_e64 v57, v57, v0, s[94:95]
	v_cndmask_b32_e64 v84, v84, v0, s[62:63]
	v_readlane_b32 s62, v253, 51
	v_readlane_b32 s63, v253, 52
	v_cndmask_b32_e64 v58, v58, v0, s[96:97]
	v_cndmask_b32_e64 v59, v59, v0, s[4:5]
	v_cndmask_b32_e64 v85, v85, v0, s[62:63]
	v_readlane_b32 s62, v253, 63
	v_readlane_b32 s63, v254, 0
	v_cndmask_b32_e64 v60, v60, v0, s[6:7]
	v_cndmask_b32_e64 v61, v61, v0, s[0:1]
	v_cndmask_b32_e64 v86, v86, v0, s[62:63]
	v_readlane_b32 s62, v254, 35
	v_readlane_b32 s63, v254, 36
	v_cndmask_b32_e64 v62, v62, v0, s[54:55]
	v_cndmask_b32_e64 v63, v63, v0, s[10:11]
	v_cndmask_b32_e64 v87, v87, v0, s[62:63]
	v_readlane_b32 s62, v254, 39
	v_readlane_b32 s63, v254, 40
	v_cndmask_b32_e64 v64, v64, v0, s[14:15]
	v_cndmask_b32_e64 v65, v65, v0, s[16:17]
	v_cndmask_b32_e64 v88, v88, v0, s[62:63]
	v_readlane_b32 s62, v254, 43
	v_readlane_b32 s63, v254, 44
	v_cndmask_b32_e64 v66, v66, v0, s[18:19]
	v_cndmask_b32_e64 v67, v67, v0, s[68:69]
	v_cndmask_b32_e64 v89, v89, v0, s[62:63]
	v_readlane_b32 s62, v254, 47
	v_readlane_b32 s63, v254, 48
	v_cndmask_b32_e64 v68, v68, v0, s[74:75]
	v_cndmask_b32_e64 v69, v69, v0, s[76:77]
	v_cndmask_b32_e64 v90, v90, v0, s[62:63]
	v_readlane_b32 s62, v254, 51
	v_readlane_b32 s63, v254, 52
	v_cndmask_b32_e64 v70, v70, v0, s[26:27]
	v_cndmask_b32_e64 v71, v71, v0, s[28:29]
	v_cndmask_b32_e64 v91, v91, v0, s[62:63]
	v_readlane_b32 s62, v254, 3
	v_readlane_b32 s63, v254, 4
	v_cndmask_b32_e64 v72, v72, v0, s[30:31]
	v_cndmask_b32_e64 v73, v73, v0, s[34:35]
	v_cndmask_b32_e64 v92, v92, v0, s[62:63]
	v_readlane_b32 s62, v254, 5
	v_readlane_b32 s63, v254, 6
	v_cndmask_b32_e64 v74, v74, v0, s[36:37]
	v_cndmask_b32_e64 v75, v75, v0, s[38:39]
	v_cndmask_b32_e64 v93, v93, v0, s[62:63]
	v_readlane_b32 s62, v254, 7
	v_readlane_b32 s63, v254, 8
	v_cndmask_b32_e64 v76, v76, v0, s[40:41]
	v_cndmask_b32_e64 v77, v77, v0, s[42:43]
	v_cndmask_b32_e64 v94, v94, v0, s[62:63]
	v_readlane_b32 s62, v254, 9
	v_readlane_b32 s63, v254, 10
	v_cndmask_b32_e64 v78, v78, v0, s[44:45]
	v_cndmask_b32_e64 v79, v79, v0, s[46:47]
	v_cndmask_b32_e64 v95, v95, v0, s[62:63]
	v_readlane_b32 s62, v254, 11
	v_readlane_b32 s63, v254, 12
	s_nop 1
	v_cndmask_b32_e64 v96, v96, v0, s[62:63]
	v_readlane_b32 s62, v254, 13
	v_readlane_b32 s63, v254, 14
	s_nop 1
	v_cndmask_b32_e64 v97, v97, v0, s[62:63]
	v_readlane_b32 s62, v254, 15
	v_readlane_b32 s63, v254, 16
	s_nop 1
	v_cndmask_b32_e64 v98, v98, v0, s[62:63]
	v_readlane_b32 s62, v254, 17
	v_readlane_b32 s63, v254, 18
	s_nop 1
	v_cndmask_b32_e64 v99, v99, v0, s[62:63]
	v_readlane_b32 s62, v254, 19
	v_readlane_b32 s63, v254, 20
	s_nop 1
	v_cndmask_b32_e64 v100, v100, v0, s[62:63]
	v_readlane_b32 s62, v254, 21
	v_readlane_b32 s63, v254, 22
	s_nop 1
	v_cndmask_b32_e64 v101, v101, v0, s[62:63]
	v_readlane_b32 s62, v254, 23
	v_readlane_b32 s63, v254, 24
	s_nop 1
	v_cndmask_b32_e64 v102, v102, v0, s[62:63]
	v_readlane_b32 s62, v254, 25
	v_readlane_b32 s63, v254, 26
	s_nop 1
	v_cndmask_b32_e64 v103, v103, v0, s[62:63]
	v_readlane_b32 s62, v254, 27
	v_readlane_b32 s63, v254, 28
	s_nop 1
	v_cndmask_b32_e64 v104, v104, v0, s[62:63]
	v_readlane_b32 s62, v254, 29
	v_readlane_b32 s63, v254, 30
	s_nop 1
	v_cndmask_b32_e64 v105, v105, v0, s[62:63]
	v_readlane_b32 s62, v254, 31
	v_readlane_b32 s63, v254, 32
	s_nop 1
	v_cndmask_b32_e64 v106, v106, v0, s[62:63]
	v_readlane_b32 s62, v254, 33
	v_readlane_b32 s63, v254, 34
	s_nop 1
	v_cndmask_b32_e64 v107, v107, v0, s[62:63]
	v_readlane_b32 s62, v254, 37
	v_readlane_b32 s63, v254, 38
	s_nop 1
	v_cndmask_b32_e64 v108, v108, v0, s[62:63]
	v_readlane_b32 s62, v254, 41
	v_readlane_b32 s63, v254, 42
	s_nop 1
	v_cndmask_b32_e64 v109, v109, v0, s[62:63]
	v_readlane_b32 s62, v254, 45
	v_readlane_b32 s63, v254, 46
	s_nop 1
	v_cndmask_b32_e64 v110, v110, v0, s[62:63]
	v_readlane_b32 s62, v254, 49
	v_readlane_b32 s63, v254, 50
	s_nop 1
	v_cndmask_b32_e64 v111, v111, v0, s[62:63]
	v_readlane_b32 s62, v254, 53
	v_readlane_b32 s63, v254, 54
	s_nop 1
	v_cndmask_b32_e64 v48, v48, v0, s[62:63]
	v_readlane_b32 s62, v254, 55
	v_readlane_b32 s63, v254, 56
	s_nop 1
	v_cndmask_b32_e64 v49, v49, v0, s[62:63]
	v_readlane_b32 s62, v254, 57
	v_readlane_b32 s63, v254, 58
	s_nop 1
	v_cndmask_b32_e64 v50, v50, v0, s[62:63]
	v_readlane_b32 s62, v254, 59
	v_readlane_b32 s63, v254, 60
	s_nop 1
	v_cndmask_b32_e64 v51, v51, v0, s[62:63]
	v_max3_f32 v241, v80, v81, v82
	v_max3_f32 v241, v241, v83, v84
	v_max3_f32 v241, v241, v85, v86
	v_max3_f32 v241, v241, v87, v88
	v_max3_f32 v241, v241, v89, v90
	v_max3_f32 v241, v241, v91, v92
	v_max3_f32 v241, v241, v93, v94
	v_max_f32_e32 v241, v241, v95
	v_max3_f32 v242, v96, v97, v98
	v_max3_f32 v242, v242, v99, v100
	v_max3_f32 v242, v242, v101, v102
	v_max3_f32 v242, v242, v103, v104
	v_max3_f32 v242, v242, v105, v106
	v_max3_f32 v242, v242, v107, v108
	v_max3_f32 v242, v242, v109, v110
	v_max_f32_e32 v242, v242, v111
	v_max3_f32 v243, v48, v49, v50
	v_max3_f32 v243, v243, v51, v52
	v_max3_f32 v243, v243, v53, v54
	v_max3_f32 v243, v243, v55, v56
	v_max3_f32 v243, v243, v57, v58
	v_max3_f32 v243, v243, v59, v60
	v_max3_f32 v243, v243, v61, v62
	v_max_f32_e32 v243, v243, v63

.LBB0_279:
	s_andn2_b64 vcc, exec, s[56:57]
	s_cbranch_vccnz .LBB0_240
	s_add_i32 s2, s81, -3
	s_cmp_gt_u32 s2, s78
	s_cbranch_scc1 .LBB0_240
	v_readlane_b32 s48, v253, 7
	v_readlane_b32 s49, v253, 8
	s_mov_b32 s51, s49
	s_min_i32 s50, s81, s78
	s_lshl_b64 s[48:49], s[50:51], 17
	v_lshl_add_u64 v[2:3], v[200:201], 0, s[48:49]
	v_add_co_u32_e32 v4, vcc, 0x10000, v2
	s_lshl_b64 s[48:49], s[50:51], 13
	s_nop 0
	v_addc_co_u32_e32 v5, vcc, 0, v3, vcc
	global_load_dwordx4 v[144:147], v[2:3], off
	global_load_dwordx4 v[156:159], v[4:5], off
	v_lshl_add_u64 v[2:3], v[202:203], 0, s[48:49]
	s_lshl_b64 s[48:49], s[50:51], 8
	global_load_dwordx4 v[164:167], v[2:3], off
	v_lshl_add_u64 v[2:3], v[204:205], 0, s[48:49]
	v_add_co_u32_e32 v4, vcc, 0x82000, v2
	s_mov_b32 s3, s51
	s_nop 0
	v_addc_co_u32_e32 v5, vcc, 0, v3, vcc
	global_load_dwordx4 v[168:171], v[2:3], off
	global_load_dwordx4 v[172:175], v[4:5], off
	v_writelane_b32 v253, s2, 7
	s_nop 1
	v_cmp_le_i32_e32 vcc, s2, v199
	v_writelane_b32 v253, s3, 8
	s_and_b64 s[48:49], s[64:65], vcc
	s_and_saveexec_b64 s[56:57], s[48:49]
	s_cbranch_execz .LBB0_239
	s_mul_i32 s59, s59, 0xac00
	v_or_b32_e32 v239, s59, v196
	v_add_u32_e32 v240, v239, v229
	ds_read_b128 v[2:5], v240
	ds_read_b128 v[6:9], v240 offset:32
	v_cmp_ge_i32_e32 vcc, s2, v199
	s_waitcnt lgkmcnt(1)
	v_mfma_f32_32x32x16_bf16 v[80:95], v[2:5], v[112:115], 0
	v_cndmask_b32_e32 v1, 3, v228, vcc
	s_waitcnt lgkmcnt(0)
	v_mfma_f32_32x32x16_bf16 v[80:95], v[6:9], v[116:119], v[80:95]
	ds_read_b128 v[2:5], v240 offset:64
	ds_read_b128 v[6:9], v240 offset:96
	s_waitcnt lgkmcnt(1)
	v_mfma_f32_32x32x16_bf16 v[80:95], v[2:5], v[120:123], v[80:95]
	ds_read_b128 v[2:5], v240 offset:128
	v_cmp_ne_u32_e64 s[52:53], 0, v1
	s_waitcnt lgkmcnt(1)
	v_mfma_f32_32x32x16_bf16 v[80:95], v[6:9], v[124:127], v[80:95]
	ds_read_b128 v[6:9], v240 offset:160
	s_waitcnt lgkmcnt(1)
	v_mfma_f32_32x32x16_bf16 v[80:95], v[2:5], v[128:131], v[80:95]
	s_waitcnt lgkmcnt(0)
	v_mfma_f32_32x32x16_bf16 v[80:95], v[6:9], v[132:135], v[80:95]
	s_and_saveexec_b64 s[48:49], s[52:53]
	s_cbranch_execz .Lmla_init_6
	ds_read_b128 v[2:5], v240 offset:6656
	ds_read_b128 v[212:215], v240 offset:6688
	ds_read_b128 v[216:219], v240 offset:6720
	ds_read_b128 v[220:223], v240 offset:6752
	s_waitcnt lgkmcnt(3)
	v_mfma_f32_32x32x16_bf16 v[96:111], v[2:5], v[112:115], 0
	ds_read_b128 v[2:5], v240 offset:6784
	s_waitcnt lgkmcnt(3)
	v_mfma_f32_32x32x16_bf16 v[96:111], v[212:215], v[116:119], v[96:111]
	ds_read_b128 v[212:215], v240 offset:6816
	s_waitcnt lgkmcnt(3)
	v_mfma_f32_32x32x16_bf16 v[96:111], v[216:219], v[120:123], v[96:111]
	v_max3_f32 v241, v80, v81, v82
	v_max3_f32 v241, v241, v83, v84
	s_waitcnt lgkmcnt(2)
	v_mfma_f32_32x32x16_bf16 v[96:111], v[220:223], v[124:127], v[96:111]
	v_max3_f32 v241, v241, v85, v86
	v_max3_f32 v241, v241, v87, v88
	s_waitcnt lgkmcnt(1)
	v_mfma_f32_32x32x16_bf16 v[96:111], v[2:5], v[128:131], v[96:111]
	v_max3_f32 v241, v241, v89, v90
	v_max3_f32 v241, v241, v91, v92
	s_waitcnt lgkmcnt(0)
	v_mfma_f32_32x32x16_bf16 v[96:111], v[212:215], v[132:135], v[96:111]
	v_max3_f32 v241, v241, v93, v94
	v_max_f32_e32 v241, v241, v95

.LBB0_288:
	s_or_b64 exec, exec, s[62:63]
	s_movk_i32 s2, 0x43
	v_cmp_eq_u32_e32 vcc, s2, v233
	s_and_saveexec_b64 s[64:65], vcc
	s_cbranch_execz .LBB0_290
	v_readlane_b32 s2, v253, 53
	v_readlane_b32 s3, v253, 54
	v_cndmask_b32_e64 v81, v0, v81, s[12:13]
	v_cndmask_b32_e64 v52, v52, v0, s[84:85]
	v_cndmask_b32_e64 v1, v80, v0, s[2:3]
	v_readlane_b32 s2, v253, 55
	v_readlane_b32 s3, v253, 56
	v_cndmask_b32_e64 v80, v1, v80, s[12:13]
	v_cndmask_b32_e64 v53, v53, v0, s[86:87]
	v_cndmask_b32_e64 v82, v82, v0, s[2:3]
	v_readlane_b32 s2, v253, 57
	v_readlane_b32 s3, v253, 58
	v_cndmask_b32_e64 v54, v54, v0, s[88:89]
	v_cndmask_b32_e64 v55, v55, v0, s[90:91]
	v_cndmask_b32_e64 v83, v83, v0, s[2:3]
	v_readlane_b32 s2, v253, 61
	v_readlane_b32 s3, v253, 62
	v_cndmask_b32_e64 v56, v56, v0, s[92:93]
	v_cndmask_b32_e64 v57, v57, v0, s[94:95]
	v_cndmask_b32_e64 v84, v84, v0, s[2:3]
	v_readlane_b32 s2, v253, 51
	v_readlane_b32 s3, v253, 52
	v_cndmask_b32_e64 v58, v58, v0, s[96:97]
	v_cndmask_b32_e64 v59, v59, v0, s[4:5]
	v_cndmask_b32_e64 v85, v85, v0, s[2:3]
	v_readlane_b32 s2, v253, 63
	v_readlane_b32 s3, v254, 0
	v_cndmask_b32_e64 v60, v60, v0, s[6:7]
	v_cndmask_b32_e64 v61, v61, v0, s[0:1]
	v_cndmask_b32_e64 v86, v86, v0, s[2:3]
	v_readlane_b32 s2, v254, 35
	v_readlane_b32 s3, v254, 36
	v_cndmask_b32_e64 v62, v62, v0, s[54:55]
	v_cndmask_b32_e64 v63, v63, v0, s[10:11]
	v_cndmask_b32_e64 v87, v87, v0, s[2:3]
	v_readlane_b32 s2, v254, 39
	v_readlane_b32 s3, v254, 40
	v_cndmask_b32_e64 v64, v64, v0, s[14:15]
	v_cndmask_b32_e64 v65, v65, v0, s[16:17]
	v_cndmask_b32_e64 v88, v88, v0, s[2:3]
	v_readlane_b32 s2, v254, 43
	v_readlane_b32 s3, v254, 44
	v_cndmask_b32_e64 v66, v66, v0, s[18:19]
	v_cndmask_b32_e64 v67, v67, v0, s[68:69]
	v_cndmask_b32_e64 v89, v89, v0, s[2:3]
	v_readlane_b32 s2, v254, 47
	v_readlane_b32 s3, v254, 48
	v_cndmask_b32_e64 v68, v68, v0, s[74:75]
	v_cndmask_b32_e64 v69, v69, v0, s[76:77]
	v_cndmask_b32_e64 v90, v90, v0, s[2:3]
	v_readlane_b32 s2, v254, 51
	v_readlane_b32 s3, v254, 52
	v_cndmask_b32_e64 v70, v70, v0, s[26:27]
	v_cndmask_b32_e64 v71, v71, v0, s[28:29]
	v_cndmask_b32_e64 v91, v91, v0, s[2:3]
	v_readlane_b32 s2, v254, 3
	v_readlane_b32 s3, v254, 4
	v_cndmask_b32_e64 v72, v72, v0, s[30:31]
	v_cndmask_b32_e64 v73, v73, v0, s[34:35]
	v_cndmask_b32_e64 v92, v92, v0, s[2:3]
	v_readlane_b32 s2, v254, 5
	v_readlane_b32 s3, v254, 6
	v_cndmask_b32_e64 v74, v74, v0, s[36:37]
	v_cndmask_b32_e64 v75, v75, v0, s[38:39]
	v_cndmask_b32_e64 v93, v93, v0, s[2:3]
	v_readlane_b32 s2, v254, 7
	v_readlane_b32 s3, v254, 8
	v_cndmask_b32_e64 v76, v76, v0, s[40:41]
	v_cndmask_b32_e64 v77, v77, v0, s[42:43]
	v_cndmask_b32_e64 v94, v94, v0, s[2:3]
	v_readlane_b32 s2, v254, 9
	v_readlane_b32 s3, v254, 10
	v_cndmask_b32_e64 v78, v78, v0, s[44:45]
	v_cndmask_b32_e64 v79, v79, v0, s[46:47]
	v_cndmask_b32_e64 v95, v95, v0, s[2:3]
	v_readlane_b32 s2, v254, 11
	v_readlane_b32 s3, v254, 12
	s_nop 1
	v_cndmask_b32_e64 v96, v96, v0, s[2:3]
	v_readlane_b32 s2, v254, 13
	v_readlane_b32 s3, v254, 14
	s_nop 1
	v_cndmask_b32_e64 v97, v97, v0, s[2:3]
	v_readlane_b32 s2, v254, 15
	v_readlane_b32 s3, v254, 16
	s_nop 1
	v_cndmask_b32_e64 v98, v98, v0, s[2:3]
	v_readlane_b32 s2, v254, 17
	v_readlane_b32 s3, v254, 18
	s_nop 1
	v_cndmask_b32_e64 v99, v99, v0, s[2:3]
	v_readlane_b32 s2, v254, 19
	v_readlane_b32 s3, v254, 20
	s_nop 1
	v_cndmask_b32_e64 v100, v100, v0, s[2:3]
	v_readlane_b32 s2, v254, 21
	v_readlane_b32 s3, v254, 22
	s_nop 1
	v_cndmask_b32_e64 v101, v101, v0, s[2:3]
	v_readlane_b32 s2, v254, 23
	v_readlane_b32 s3, v254, 24
	s_nop 1
	v_cndmask_b32_e64 v102, v102, v0, s[2:3]
	v_readlane_b32 s2, v254, 25
	v_readlane_b32 s3, v254, 26
	s_nop 1
	v_cndmask_b32_e64 v103, v103, v0, s[2:3]
	v_readlane_b32 s2, v254, 27
	v_readlane_b32 s3, v254, 28
	s_nop 1
	v_cndmask_b32_e64 v104, v104, v0, s[2:3]
	v_readlane_b32 s2, v254, 29
	v_readlane_b32 s3, v254, 30
	s_nop 1
	v_cndmask_b32_e64 v105, v105, v0, s[2:3]
	v_readlane_b32 s2, v254, 31
	v_readlane_b32 s3, v254, 32
	s_nop 1
	v_cndmask_b32_e64 v106, v106, v0, s[2:3]
	v_readlane_b32 s2, v254, 33
	v_readlane_b32 s3, v254, 34
	s_nop 1
	v_cndmask_b32_e64 v107, v107, v0, s[2:3]
	v_readlane_b32 s2, v254, 37
	v_readlane_b32 s3, v254, 38
	s_nop 1
	v_cndmask_b32_e64 v108, v108, v0, s[2:3]
	v_readlane_b32 s2, v254, 41
	v_readlane_b32 s3, v254, 42
	s_nop 1
	v_cndmask_b32_e64 v109, v109, v0, s[2:3]
	v_readlane_b32 s2, v254, 45
	v_readlane_b32 s3, v254, 46
	s_nop 1
	v_cndmask_b32_e64 v110, v110, v0, s[2:3]
	v_readlane_b32 s2, v254, 49
	v_readlane_b32 s3, v254, 50
	s_nop 1
	v_cndmask_b32_e64 v111, v111, v0, s[2:3]
	v_readlane_b32 s2, v254, 53
	v_readlane_b32 s3, v254, 54
	s_nop 1
	v_cndmask_b32_e64 v48, v48, v0, s[2:3]
	v_readlane_b32 s2, v254, 55
	v_readlane_b32 s3, v254, 56
	s_nop 1
	v_cndmask_b32_e64 v49, v49, v0, s[2:3]
	v_readlane_b32 s2, v254, 57
	v_readlane_b32 s3, v254, 58
	s_nop 1
	v_cndmask_b32_e64 v50, v50, v0, s[2:3]
	v_readlane_b32 s2, v254, 59
	v_readlane_b32 s3, v254, 60
	s_nop 1
	v_cndmask_b32_e64 v51, v51, v0, s[2:3]
	v_max3_f32 v241, v80, v81, v82
	v_max3_f32 v241, v241, v83, v84
	v_max3_f32 v241, v241, v85, v86
	v_max3_f32 v241, v241, v87, v88
	v_max3_f32 v241, v241, v89, v90
	v_max3_f32 v241, v241, v91, v92
	v_max3_f32 v241, v241, v93, v94
	v_max_f32_e32 v241, v241, v95
	v_max3_f32 v242, v96, v97, v98
	v_max3_f32 v242, v242, v99, v100
	v_max3_f32 v242, v242, v101, v102
	v_max3_f32 v242, v242, v103, v104
	v_max3_f32 v242, v242, v105, v106
	v_max3_f32 v242, v242, v107, v108
	v_max3_f32 v242, v242, v109, v110
	v_max_f32_e32 v242, v242, v111
	v_max3_f32 v243, v48, v49, v50
	v_max3_f32 v243, v243, v51, v52
	v_max3_f32 v243, v243, v53, v54
	v_max3_f32 v243, v243, v55, v56
	v_max3_f32 v243, v243, v57, v58
	v_max3_f32 v243, v243, v59, v60
	v_max3_f32 v243, v243, v61, v62
	v_max_f32_e32 v243, v243, v63
.LBB0_290:
	s_or_b64 exec, exec, s[64:65]
	s_nop 3
	v_max3_f32 v4, v64, v65, v66
	v_max3_f32 v4, v4, v67, v68
	v_max3_f32 v4, v4, v69, v70
	v_max3_f32 v4, v4, v71, v72
	v_max3_f32 v4, v4, v73, v74
	v_max3_f32 v4, v4, v75, v76
	v_max3_f32 v4, v4, v77, v78
	v_max_f32_e32 v4, v4, v79
	v_max3_f32 v1, v241, v242, v243
	v_max_f32_e32 v1, v1, v4
	v_mov_b32_e32 v2, v1
	s_nop 1
	v_permlane32_swap_b32_e32 v2, v1
	s_nop 0
	v_max3_f32 v1, v238, v1, v2
	v_sub_f32_e32 v2, v238, v1
	v_exp_f32_e32 v2, v2
	v_cmp_gt_f32_e32 vcc, v1, v238
	s_cbranch_vccz .LBB0_292
	v_pk_mul_f32 v[46:47], v[46:47], v[2:3] op_sel_hi:[1,0]
	v_pk_mul_f32 v[44:45], v[44:45], v[2:3] op_sel_hi:[1,0]
	v_pk_mul_f32 v[42:43], v[42:43], v[2:3] op_sel_hi:[1,0]
	v_pk_mul_f32 v[40:41], v[40:41], v[2:3] op_sel_hi:[1,0]
	v_pk_mul_f32 v[38:39], v[38:39], v[2:3] op_sel_hi:[1,0]
	v_pk_mul_f32 v[36:37], v[36:37], v[2:3] op_sel_hi:[1,0]
	v_pk_mul_f32 v[34:35], v[34:35], v[2:3] op_sel_hi:[1,0]
	v_pk_mul_f32 v[32:33], v[32:33], v[2:3] op_sel_hi:[1,0]
	v_pk_mul_f32 v[30:31], v[30:31], v[2:3] op_sel_hi:[1,0]
	v_pk_mul_f32 v[28:29], v[28:29], v[2:3] op_sel_hi:[1,0]
	v_pk_mul_f32 v[26:27], v[26:27], v[2:3] op_sel_hi:[1,0]
	v_pk_mul_f32 v[24:25], v[24:25], v[2:3] op_sel_hi:[1,0]
	v_pk_mul_f32 v[22:23], v[22:23], v[2:3] op_sel_hi:[1,0]
	v_pk_mul_f32 v[20:21], v[20:21], v[2:3] op_sel_hi:[1,0]
	v_pk_mul_f32 v[18:19], v[18:19], v[2:3] op_sel_hi:[1,0]
	v_pk_mul_f32 v[16:17], v[16:17], v[2:3] op_sel_hi:[1,0]

.Lmla_init_0:
	s_or_b64 exec, exec, s[48:49]
	v_mov_b32_e32 v96, v0
	v_mov_b32_e32 v97, v0
	v_mov_b32_e32 v98, v0
	v_mov_b32_e32 v99, v0
	v_mov_b32_e32 v100, v0
	v_mov_b32_e32 v101, v0
	v_mov_b32_e32 v102, v0
	v_mov_b32_e32 v103, v0
	v_mov_b32_e32 v104, v0
	v_mov_b32_e32 v105, v0
	v_mov_b32_e32 v106, v0
	v_mov_b32_e32 v107, v0
	v_mov_b32_e32 v108, v0
	v_mov_b32_e32 v109, v0
	v_mov_b32_e32 v110, v0
	v_mov_b32_e32 v111, v0
	v_max3_f32 v241, v80, v81, v82
	v_max3_f32 v241, v241, v83, v84
	v_max3_f32 v241, v241, v85, v86
	v_max3_f32 v241, v241, v87, v88
	v_max3_f32 v241, v241, v89, v90
	v_max3_f32 v241, v241, v91, v92
	v_max3_f32 v241, v241, v93, v94
	v_max_f32_e32 v241, v241, v95
	s_branch .LBB0_244
.Lmla_init_1:
	s_or_b64 exec, exec, s[48:49]
	v_mov_b32_e32 v48, v0
	v_mov_b32_e32 v49, v0
	v_mov_b32_e32 v50, v0
	v_mov_b32_e32 v51, v0
	v_mov_b32_e32 v52, v0
	v_mov_b32_e32 v53, v0
	v_mov_b32_e32 v54, v0
	v_mov_b32_e32 v55, v0
	v_mov_b32_e32 v56, v0
	v_mov_b32_e32 v57, v0
	v_mov_b32_e32 v58, v0
	v_mov_b32_e32 v59, v0
	v_mov_b32_e32 v60, v0
	v_mov_b32_e32 v61, v0
	v_mov_b32_e32 v62, v0
	v_mov_b32_e32 v63, v0
	v_max3_f32 v242, v96, v97, v98
	v_max3_f32 v242, v242, v99, v100
	v_max3_f32 v242, v242, v101, v102
	v_max3_f32 v242, v242, v103, v104
	v_max3_f32 v242, v242, v105, v106
	v_max3_f32 v242, v242, v107, v108
	v_max3_f32 v242, v242, v109, v110
	v_max_f32_e32 v242, v242, v111
	s_branch .LBB0_246
.Lmla_init_2:
	s_or_b64 exec, exec, s[56:57]
	v_mov_b32_e32 v64, v0
	v_mov_b32_e32 v65, v0
	v_mov_b32_e32 v66, v0
	v_mov_b32_e32 v67, v0
	v_mov_b32_e32 v68, v0
	v_mov_b32_e32 v69, v0
	v_mov_b32_e32 v70, v0
	v_mov_b32_e32 v71, v0
	v_mov_b32_e32 v72, v0
	v_mov_b32_e32 v73, v0
	v_mov_b32_e32 v74, v0
	v_mov_b32_e32 v75, v0
	v_mov_b32_e32 v76, v0
	v_mov_b32_e32 v77, v0
	v_mov_b32_e32 v78, v0
	v_mov_b32_e32 v79, v0
	v_max3_f32 v243, v48, v49, v50
	v_max3_f32 v243, v243, v51, v52
	v_max3_f32 v243, v243, v53, v54
	v_max3_f32 v243, v243, v55, v56
	v_max3_f32 v243, v243, v57, v58
	v_max3_f32 v243, v243, v59, v60
	v_max3_f32 v243, v243, v61, v62
	v_max_f32_e32 v243, v243, v63
	s_branch .LBB0_248

.Lmla_init_5:
	s_or_b64 exec, exec, s[62:63]
	v_mov_b32_e32 v64, v0
	v_mov_b32_e32 v65, v0
	v_mov_b32_e32 v66, v0
	v_mov_b32_e32 v67, v0
	v_mov_b32_e32 v68, v0
	v_mov_b32_e32 v69, v0
	v_mov_b32_e32 v70, v0
	v_mov_b32_e32 v71, v0
	v_mov_b32_e32 v72, v0
	v_mov_b32_e32 v73, v0
	v_mov_b32_e32 v74, v0
	v_mov_b32_e32 v75, v0
	v_mov_b32_e32 v76, v0
	v_mov_b32_e32 v77, v0
	v_mov_b32_e32 v78, v0
	v_mov_b32_e32 v79, v0
	v_max3_f32 v243, v48, v49, v50
	v_max3_f32 v243, v243, v51, v52
	v_max3_f32 v243, v243, v53, v54
	v_max3_f32 v243, v243, v55, v56
	v_max3_f32 v243, v243, v57, v58
	v_max3_f32 v243, v243, v59, v60
	v_max3_f32 v243, v243, v61, v62
	v_max_f32_e32 v243, v243, v63
	s_branch .LBB0_267
